# XCD-aware tile remap for N=1024 residual GEMMs (out-proj, ffn-down, ctx tails): 8 column tiles of one A row-block on one XCD
# speedup vs baseline: 1.0055x; 1.0055x over previous
; DI int bid_l() { int t = blockIdx.x; asm volatile("" : "+s"(t)); return t; }
; DI f32x16 zero16() { f32x16 z; for (int i = 0; i < 16; ++i) z[i] = 0.f; return z; }
; template <int MF, int BK, class Epi>
; DI void gemm_phase_t(char* lds, const GemmDesc g, const Epi epi) {
;     ...
;   for (int t = bid_l(); t < ntiles; t += gridDim.x) {
;     const int tn = t % ntn, tm = t / ntn;
;     const int m0 = tm * BM, n0 = tn * 128;
;     const u16* Ap = g.A + (size_t)(m0 + lr) * g.lda + lc * 8;
;     const u16* Bp = g.Bt + (size_t)(n0 + lr) * g.ldb + lc * 8;
;     u32x4 ra[APT], rb[BPT];
; #pragma unroll
;     for (int j = 0; j < APT; ++j) ra[j] = *(const u32x4*)(Ap + (size_t)j * RSTEP * g.lda);
; #pragma unroll
;     for (int j = 0; j < BPT; ++j) rb[j] = *(const u32x4*)(Bp + (size_t)j * RSTEP * g.ldb);
; #pragma unroll
;     for (int j = 0; j < APT; ++j) *(u32x4*)(sbase + (lr + RSTEP * j) * LS + lc * 8) = ra[j];
; #pragma unroll
;     for (int j = 0; j < BPT; ++j) *(u32x4*)(sbase + BM * LS + (lr + RSTEP * j) * LS + lc * 8) = rb[j];
;     if (nk > 1) {
; #pragma unroll
;       for (int j = 0; j < APT; ++j) ra[j] = *(const u32x4*)(Ap + (size_t)j * RSTEP * g.lda + BK);
; #pragma unroll
;       for (int j = 0; j < BPT; ++j) rb[j] = *(const u32x4*)(Bp + (size_t)j * RSTEP * g.ldb + BK);
;     }
;     f32x16 acc[MF][2];
; #pragma unroll
;     for (int i = 0; i < MF; ++i)
; #pragma unroll
;       for (int j = 0; j < 2; ++j) acc[i][j] = zero16();
.LBB0_34:
	s_mov_b32 s98, s6
	v_readlane_b32 s99, v252, 40
	s_cmpk_lg_i32 s99, 0x200
	s_cbranch_scc1 .Lnomap_tl1
	s_and_b32 s98, s6, 7
	s_lshl_b32 s98, s98, 3
	s_bfe_u32 s99, s6, 0x30006
	s_add_i32 s98, s98, s99
	s_lshr_b32 s99, s6, 9
	s_lshl_b32 s99, s99, 6
	s_add_i32 s98, s98, s99
	s_lshl_b32 s98, s98, 3
	s_bfe_u32 s99, s6, 0x30003
	s_or_b32 s98, s98, s99
.Lnomap_tl1:
	s_ashr_i32 s7, s98, 31
	s_lshr_b32 s7, s7, 29
	s_add_i32 s7, s98, s7
	s_and_b32 s8, s7, 0x1fffff8
	s_lshl_b32 s7, s7, 4
	s_and_b32 s7, s7, 0xffffff80
	v_add_u32_e32 v58, s7, v2
	s_movk_i32 s12, 0x1600
	v_mad_i64_i32 v[4:5], s[10:11], v58, s12, v[102:103]
	v_add_co_u32_e32 v6, vcc, 0x2c000, v4
	s_sub_i32 s8, s98, s8
	s_nop 0
	v_addc_co_u32_e32 v7, vcc, 0, v5, vcc
	s_lshl_b32 s8, s8, 7
	v_add_co_u32_e32 v8, vcc, 0x58000, v4
	v_add_u32_e32 v59, s8, v2
	s_nop 0
	v_addc_co_u32_e32 v9, vcc, 0, v5, vcc
	global_load_dwordx4 v[26:29], v[4:5], off
	global_load_dwordx4 v[30:33], v[6:7], off
	v_add_co_u32_e32 v10, vcc, 0x84000, v4
	s_waitcnt vmcnt(3)
	v_mad_i64_i32 v[12:13], s[10:11], v59, s12, v[104:105]
	v_addc_co_u32_e32 v11, vcc, 0, v5, vcc
	global_load_dwordx4 v[42:45], v[12:13], off
	s_mov_b32 s9, 0x2c000
	v_add_co_u32_e32 v14, vcc, s9, v12
	global_load_dwordx4 v[34:37], v[8:9], off
	global_load_dwordx4 v[38:41], v[10:11], off
	v_addc_co_u32_e32 v15, vcc, 0, v13, vcc
	s_mov_b32 s9, 0x58000
	v_add_co_u32_e32 v16, vcc, s9, v12
	global_load_dwordx4 v[46:49], v[14:15], off
	s_nop 0
	v_addc_co_u32_e32 v17, vcc, 0, v13, vcc
	s_mov_b32 s9, 0x84000
	global_load_dwordx4 v[50:53], v[16:17], off
	v_add_co_u32_e32 v18, vcc, s9, v12
	v_mad_i64_i32 v[108:109], s[10:11], v58, s12, v[100:101]
	s_nop 0
	v_addc_co_u32_e32 v19, vcc, 0, v13, vcc
	global_load_dwordx4 v[54:57], v[18:19], off
	global_load_dwordx4 v[68:71], v[16:17], off offset:128
	global_load_dwordx4 v[72:75], v[14:15], off offset:128
	global_load_dwordx4 v[76:79], v[12:13], off offset:128
	global_load_dwordx4 v[80:83], v[10:11], off offset:128
	global_load_dwordx4 v[88:91], v[8:9], off offset:128
	global_load_dwordx4 v[92:95], v[6:7], off offset:128
	global_load_dwordx4 v[96:99], v[4:5], off offset:128
	global_load_dwordx4 v[84:87], v[18:19], off offset:128
	v_mov_b32_e32 v4, 0
	v_mad_i64_i32 v[110:111], s[10:11], v59, s12, v[106:107]
	s_mov_b32 s9, 42
	v_mov_b32_e32 v5, v4
	v_mov_b32_e32 v6, v4
	v_mov_b32_e32 v7, v4
	v_mov_b32_e32 v8, v4
	v_mov_b32_e32 v9, v4
	v_mov_b32_e32 v10, v4
	v_mov_b32_e32 v11, v4
	v_mov_b32_e32 v12, v4
	v_mov_b32_e32 v13, v4
	v_mov_b32_e32 v14, v4
	v_mov_b32_e32 v15, v4
	v_mov_b32_e32 v16, v4
	v_mov_b32_e32 v17, v4
	v_mov_b32_e32 v18, v4
	v_mov_b32_e32 v19, v4
	v_mov_b32_e32 v20, v4
	v_mov_b32_e32 v21, v4
	v_mov_b32_e32 v22, v4
	v_mov_b32_e32 v23, v4
	v_mov_b32_e32 v24, v4
	v_mov_b32_e32 v25, v4
	v_mov_b32_e32 v58, v4
	v_mov_b32_e32 v59, v4
	v_mov_b32_e32 v60, v4
	v_mov_b32_e32 v61, v4
	v_mov_b32_e32 v62, v4
	v_mov_b32_e32 v63, v4
	v_mov_b32_e32 v64, v4
	v_mov_b32_e32 v65, v4
	v_mov_b32_e32 v66, v4
	v_mov_b32_e32 v67, v4
	s_mov_b32 s11, 0x214c000
	s_mov_b32 s12, 0x2178000
	s_mov_b32 s13, 0x21a4000
	s_mov_b32 s14, 0x21d0000
	s_waitcnt vmcnt(15)
	ds_write_b128 v114, v[26:29]
	s_waitcnt vmcnt(13)
	ds_write_b128 v114, v[42:45] offset:18432
	ds_write_b128 v114, v[30:33] offset:4608
	s_waitcnt vmcnt(12)
	ds_write_b128 v114, v[34:37] offset:9216
	s_waitcnt vmcnt(11)
	ds_write_b128 v114, v[38:41] offset:13824
	s_waitcnt vmcnt(10)
	ds_write_b128 v114, v[46:49] offset:23040
	s_waitcnt vmcnt(9)
	ds_write_b128 v114, v[50:53] offset:27648
	s_waitcnt vmcnt(8)
	ds_write_b128 v114, v[54:57] offset:32256
	v_mov_b32_e32 v26, v4
	v_mov_b32_e32 v27, v4
	v_mov_b32_e32 v28, v4
	v_mov_b32_e32 v29, v4
	v_mov_b32_e32 v30, v4
	v_mov_b32_e32 v31, v4
	v_mov_b32_e32 v32, v4
	v_mov_b32_e32 v33, v4
	v_mov_b32_e32 v34, v4
	v_mov_b32_e32 v35, v4
	v_mov_b32_e32 v36, v4
	v_mov_b32_e32 v37, v4
	v_mov_b32_e32 v38, v4
	v_mov_b32_e32 v39, v4
	v_mov_b32_e32 v40, v4
	v_mov_b32_e32 v41, v4
	v_mov_b32_e32 v42, v4
	v_mov_b32_e32 v43, v4
	v_mov_b32_e32 v44, v4
	v_mov_b32_e32 v45, v4
	v_mov_b32_e32 v46, v4
	v_mov_b32_e32 v47, v4
	v_mov_b32_e32 v48, v4
	v_mov_b32_e32 v49, v4
	v_mov_b32_e32 v50, v4
	v_mov_b32_e32 v51, v4
	v_mov_b32_e32 v52, v4
	v_mov_b32_e32 v53, v4
	v_mov_b32_e32 v54, v4
	v_mov_b32_e32 v55, v4
	v_mov_b32_e32 v56, v4
	v_mov_b32_e32 v57, v4
	s_mov_b64 s[16:17], 0x100

; __device__ __forceinline__ size_t wofs(int layer) { return (layer & 1) ? W2_DELTA : (size_t)0; }
; DI int bid_l() { int t = blockIdx.x; asm volatile("" : "+s"(t)); return t; }
; template <int MF, int BK, class Epi>
; DI void gemm_phase_t(char* lds, const GemmDesc g, const Epi epi) {
;     ...
;   for (int t = bid_l(); t < ntiles; t += gridDim.x) {
;     const int tn = t % ntn, tm = t / ntn;
;     const int m0 = tm * BM, n0 = tn * 128;
; DI void run_phase(const Params& p, char* lds, int ph) {
;     ...
;       if (need_ctx) {
;         GemmDesc gc{(const u16*)(ws + OFF_ACT) + (size_t)TL * FF, FF, (const u16*)(ws + wofs(layer) + OFF_WDN), FF, TC, 1024, FF, TL};
;         gemm_phase_t<1, 64>(lds, gc, ep);
;       }
.LBB0_37:
	v_readlane_b32 s6, v253, 31
	v_readlane_b32 s7, v253, 32
	s_andn2_b64 vcc, exec, s[6:7]
	s_barrier
	s_cbranch_vccnz .LBB0_283
	v_mov_b32_e32 v2, v0
	v_readlane_b32 s6, v251, 0
	v_readlane_b32 s99, v252, 40
	s_cmpk_lg_i32 s99, 0x200
	s_cbranch_scc1 .Lnomap_c1
	s_cmpk_gt_i32 s6, 0xff
	s_cbranch_scc1 .Lnomap_c1
	s_and_b32 s98, s6, 7
	s_lshl_b32 s98, s98, 2
	s_lshr_b32 s99, s6, 6
	s_add_i32 s98, s98, s99
	s_lshl_b32 s98, s98, 3
	s_bfe_u32 s99, s6, 0x30003
	s_or_b32 s6, s98, s99
.Lnomap_c1:
	s_load_dwordx4 s[16:19], s[50:51], 0x108
	s_cmpk_gt_i32 s6, 0xff
	s_cbranch_scc1 .LBB0_43
	v_ashrrev_i32_e32 v4, 31, v2
	v_lshrrev_b32_e32 v4, 29, v4
	v_add_u32_e32 v4, v2, v4
	v_ashrrev_i32_e32 v72, 3, v4
	v_and_b32_e32 v4, -8, v4
	v_sub_u32_e32 v6, v2, v4
	v_lshlrev_b32_e32 v4, 3, v6
	v_ashrrev_i32_e32 v5, 31, v4
	v_lshlrev_b64 v[4:5], 1, v[4:5]
	v_lshl_add_u64 v[64:65], s[4:5], 0, v[4:5]
	v_ashrrev_i32_e32 v11, 2, v2
	s_movk_i32 s4, 0xffe0
	v_bfe_u32 v7, v2, 5, 1
	v_and_b32_e32 v8, 64, v2
	v_and_b32_e32 v9, 0x5f, v2
	v_bfi_b32 v2, s4, v11, v2
	s_movk_i32 s4, 0x90
	v_mul_lo_u32 v11, v2, s4
	v_add_u32_e32 v73, 0x8000, v2
	v_mul_lo_u32 v2, v72, s4
	s_waitcnt lgkmcnt(0)
	s_add_u32 s4, s18, s48
	v_lshl_add_u64 v[60:61], s[18:19], 0, v[4:5]
	s_mov_b64 s[8:9], 0xe7ac000
	v_lshlrev_b32_e32 v6, 4, v6
	v_lshlrev_b32_e32 v10, 4, v7
	v_lshl_or_b32 v74, v7, 3, v8
	v_mul_u32_u24_e32 v7, 0x90, v9
	s_addc_u32 s5, s19, 0
	v_lshl_add_u64 v[62:63], v[60:61], 0, s[8:9]
	v_lshl_add_u64 v[66:67], s[4:5], 0, v[4:5]
	v_add_u32_e32 v75, v6, v2
	v_add_u32_e32 v76, v10, v7
	v_add_u32_e32 v77, v11, v10

; DI int bid_l() { int t = blockIdx.x; asm volatile("" : "+s"(t)); return t; }
; template <int MF, int BK, class Epi>
; DI void gemm_phase_t(char* lds, const GemmDesc g, const Epi epi) {
;     ...
;   for (int t = bid_l(); t < ntiles; t += gridDim.x) {
;     const int tn = t % ntn, tm = t / ntn;
;     const int m0 = tm * BM, n0 = tn * 128;
;     const u16* Ap = g.A + (size_t)(m0 + lr) * g.lda + lc * 8;
;     const u16* Bp = g.Bt + (size_t)(n0 + lr) * g.ldb + lc * 8;
;     u32x4 ra[APT], rb[BPT];
; #pragma unroll
;     for (int j = 0; j < APT; ++j) ra[j] = *(const u32x4*)(Ap + (size_t)j * RSTEP * g.lda);
; #pragma unroll
;     for (int j = 0; j < BPT; ++j) rb[j] = *(const u32x4*)(Bp + (size_t)j * RSTEP * g.ldb);
; #pragma unroll
;     for (int j = 0; j < APT; ++j) *(u32x4*)(sbase + (lr + RSTEP * j) * LS + lc * 8) = ra[j];
; #pragma unroll
;     for (int j = 0; j < BPT; ++j) *(u32x4*)(sbase + BM * LS + (lr + RSTEP * j) * LS + lc * 8) = rb[j];
;     if (nk > 1) {
; #pragma unroll
;       for (int j = 0; j < APT; ++j) ra[j] = *(const u32x4*)(Ap + (size_t)j * RSTEP * g.lda + BK);
; #pragma unroll
;       for (int j = 0; j < BPT; ++j) rb[j] = *(const u32x4*)(Bp + (size_t)j * RSTEP * g.ldb + BK);
;     }
.LBB0_305:
	s_mov_b32 s98, s8
	v_readlane_b32 s99, v252, 40
	s_cmpk_lg_i32 s99, 0x200
	s_cbranch_scc1 .Lnomap_tl2
	s_and_b32 s98, s8, 7
	s_lshl_b32 s98, s98, 3
	s_bfe_u32 s99, s8, 0x30006
	s_add_i32 s98, s98, s99
	s_lshr_b32 s99, s8, 9
	s_lshl_b32 s99, s99, 6
	s_add_i32 s98, s98, s99
	s_lshl_b32 s98, s98, 3
	s_bfe_u32 s99, s8, 0x30003
	s_or_b32 s98, s98, s99
.Lnomap_tl2:
	s_ashr_i32 s6, s98, 31
	s_lshr_b32 s6, s6, 29
	s_add_i32 s6, s98, s6
	s_and_b32 s7, s6, 0x1fffff8
	s_lshl_b32 s6, s6, 4
	s_and_b32 s6, s6, 0xffffff80
	v_add_u32_e32 v4, s6, v2
	v_ashrrev_i32_e32 v5, 31, v4
	v_lshlrev_b64 v[36:37], 11, v[4:5]
	v_lshl_add_u64 v[38:39], v[100:101], 0, v[36:37]
	s_mov_b32 s12, 0x10000
	s_sub_i32 s7, s98, s7
	v_add_co_u32_e32 v40, vcc, s12, v38
	s_lshl_b32 s7, s7, 7
	s_nop 0
	v_addc_co_u32_e32 v41, vcc, 0, v39, vcc
	s_mov_b32 s11, 0x20000
	v_add_u32_e32 v20, s7, v2
	v_add_co_u32_e32 v42, vcc, s11, v38
	v_ashrrev_i32_e32 v21, 31, v20
	s_nop 0
	v_addc_co_u32_e32 v43, vcc, 0, v39, vcc
	s_mov_b32 s13, 0x30000
	v_add_co_u32_e32 v44, vcc, s13, v38
	v_lshlrev_b64 v[46:47], 11, v[20:21]
	global_load_dwordx4 v[4:7], v[38:39], off
	global_load_dwordx4 v[8:11], v[40:41], off
	v_addc_co_u32_e32 v45, vcc, 0, v39, vcc
	v_lshl_add_u64 v[48:49], v[102:103], 0, v[46:47]
	v_add_co_u32_e32 v50, vcc, s12, v48
	global_load_dwordx4 v[12:15], v[42:43], off
	global_load_dwordx4 v[16:19], v[44:45], off
	v_addc_co_u32_e32 v51, vcc, 0, v49, vcc
	v_add_co_u32_e32 v52, vcc, s11, v48
	global_load_dwordx4 v[20:23], v[48:49], off
	global_load_dwordx4 v[24:27], v[50:51], off
	v_addc_co_u32_e32 v53, vcc, 0, v49, vcc
	v_add_co_u32_e32 v54, vcc, s13, v48
	global_load_dwordx4 v[28:31], v[52:53], off
	s_nop 0
	v_addc_co_u32_e32 v55, vcc, 0, v49, vcc
	global_load_dwordx4 v[32:35], v[54:55], off
	v_add_u32_e32 v119, v112, v115
	v_lshl_add_u64 v[108:109], v[104:105], 0, v[46:47]
	v_lshl_add_u64 v[110:111], v[106:107], 0, v[36:37]
	s_mov_b32 s9, 14
	s_mov_b64 s[14:15], 0x100
	s_waitcnt vmcnt(7)
	ds_write_b128 v119, v[4:7]
	s_waitcnt vmcnt(6)
	ds_write_b128 v119, v[8:11] offset:4608
	s_waitcnt vmcnt(5)
	ds_write_b128 v119, v[12:15] offset:9216
	s_waitcnt vmcnt(4)
	ds_write_b128 v119, v[16:19] offset:13824
	s_waitcnt vmcnt(3)
	ds_write_b128 v119, v[20:23] offset:18432
	s_waitcnt vmcnt(2)
	ds_write_b128 v119, v[24:27] offset:23040
	s_waitcnt vmcnt(1)
	ds_write_b128 v119, v[28:31] offset:27648
	s_waitcnt vmcnt(0)
	ds_write_b128 v119, v[32:35] offset:32256
	global_load_dwordx4 v[68:71], v[54:55], off offset:128
	global_load_dwordx4 v[72:75], v[52:53], off offset:128
	global_load_dwordx4 v[76:79], v[50:51], off offset:128
	global_load_dwordx4 v[80:83], v[48:49], off offset:128
	global_load_dwordx4 v[84:87], v[44:45], off offset:128
	global_load_dwordx4 v[88:91], v[42:43], off offset:128
	global_load_dwordx4 v[92:95], v[40:41], off offset:128
	global_load_dwordx4 v[96:99], v[38:39], off offset:128
	v_mov_b32_e32 v4, 0
	v_mov_b32_e32 v5, v4
	v_mov_b32_e32 v6, v4
	v_mov_b32_e32 v7, v4
	v_mov_b32_e32 v8, v4
	v_mov_b32_e32 v9, v4
	v_mov_b32_e32 v10, v4
	v_mov_b32_e32 v11, v4
	v_mov_b32_e32 v12, v4
	v_mov_b32_e32 v13, v4
	v_mov_b32_e32 v14, v4
	v_mov_b32_e32 v15, v4
	v_mov_b32_e32 v16, v4
	v_mov_b32_e32 v17, v4
	v_mov_b32_e32 v18, v4
	v_mov_b32_e32 v19, v4
	v_mov_b32_e32 v20, v4
	v_mov_b32_e32 v21, v4
	v_mov_b32_e32 v22, v4
	v_mov_b32_e32 v23, v4
	v_mov_b32_e32 v24, v4
	v_mov_b32_e32 v25, v4
	v_mov_b32_e32 v26, v4
	v_mov_b32_e32 v27, v4
	v_mov_b32_e32 v28, v4
	v_mov_b32_e32 v29, v4
	v_mov_b32_e32 v30, v4
	v_mov_b32_e32 v31, v4
	v_mov_b32_e32 v32, v4
	v_mov_b32_e32 v33, v4
	v_mov_b32_e32 v34, v4
	v_mov_b32_e32 v35, v4
	v_mov_b32_e32 v36, v4
	v_mov_b32_e32 v37, v4
	v_mov_b32_e32 v38, v4
	v_mov_b32_e32 v39, v4
	v_mov_b32_e32 v40, v4
	v_mov_b32_e32 v41, v4
	v_mov_b32_e32 v42, v4
	v_mov_b32_e32 v43, v4
	v_mov_b32_e32 v44, v4
	v_mov_b32_e32 v45, v4
	v_mov_b32_e32 v46, v4
	v_mov_b32_e32 v47, v4
	v_mov_b32_e32 v48, v4
	v_mov_b32_e32 v49, v4
	v_mov_b32_e32 v50, v4
	v_mov_b32_e32 v51, v4
	v_mov_b32_e32 v52, v4
	v_mov_b32_e32 v53, v4
	v_mov_b32_e32 v54, v4
	v_mov_b32_e32 v55, v4
	v_mov_b32_e32 v56, v4
	v_mov_b32_e32 v57, v4
	v_mov_b32_e32 v58, v4
	v_mov_b32_e32 v59, v4
	v_mov_b32_e32 v60, v4
	v_mov_b32_e32 v61, v4
	v_mov_b32_e32 v62, v4
	v_mov_b32_e32 v63, v4
	v_mov_b32_e32 v64, v4
	v_mov_b32_e32 v65, v4
	v_mov_b32_e32 v66, v4
	v_mov_b32_e32 v67, v4

; __device__ __forceinline__ size_t wofs(int layer) { return (layer & 1) ? W2_DELTA : (size_t)0; }
; DI int bid_l() { int t = blockIdx.x; asm volatile("" : "+s"(t)); return t; }
; template <int MF, int BK, class Epi>
; DI void gemm_phase_t(char* lds, const GemmDesc g, const Epi epi) {
;     ...
;   for (int t = bid_l(); t < ntiles; t += gridDim.x) {
;     const int tn = t % ntn, tm = t / ntn;
;     const int m0 = tm * BM, n0 = tn * 128;
; DI void run_phase(const Params& p, char* lds, int ph) {
;     ...
;       if (need_ctx) {
;         GemmDesc gc{Amix + (size_t)TL * 1024, 1024, (const u16*)(ws + wofs(layer) + OFF_WOUT), 1024, TC, 1024, 1024, TL};
;         gemm_phase_t<1, 64>(lds, gc, ep);
;       }
.LBB0_308:
	v_readlane_b32 s6, v253, 31
	v_readlane_b32 s7, v253, 32
	s_andn2_b64 vcc, exec, s[6:7]
	s_barrier
	s_cbranch_vccnz .LBB0_313
	v_readlane_b32 s8, v252, 40
	v_mov_b32_e32 v2, v0
	v_readlane_b32 s6, v251, 0
	v_readlane_b32 s99, v252, 40
	s_cmpk_lg_i32 s99, 0x200
	s_cbranch_scc1 .Lnomap_c2
	s_cmpk_gt_i32 s6, 0xff
	s_cbranch_scc1 .Lnomap_c2
	s_and_b32 s98, s6, 7
	s_lshl_b32 s98, s98, 2
	s_lshr_b32 s99, s6, 6
	s_add_i32 s98, s98, s99
	s_lshl_b32 s98, s98, 3
	s_bfe_u32 s99, s6, 0x30003
	s_or_b32 s6, s98, s99
.Lnomap_c2:
	v_readlane_b32 s9, v252, 41
	v_readlane_b32 s12, v253, 28
	v_readlane_b32 s14, v253, 26
	s_cmpk_gt_i32 s6, 0xff
	s_mov_b32 s7, 0x8000
	s_mov_b32 s9, 0x20000
	s_mov_b32 s10, 0x10000
	s_mov_b32 s11, 0x30000
	v_readlane_b32 s13, v253, 29
	v_readlane_b32 s15, v253, 27
	s_cbranch_scc1 .LBB0_312
	v_ashrrev_i32_e32 v4, 31, v2
	v_lshrrev_b32_e32 v4, 29, v4
	v_add_u32_e32 v4, v2, v4
	v_ashrrev_i32_e32 v52, 3, v4
	v_and_b32_e32 v4, -8, v4
	v_sub_u32_e32 v8, v2, v4
	v_lshlrev_b32_e32 v4, 3, v8
	v_ashrrev_i32_e32 v5, 31, v4
	v_lshlrev_b64 v[4:5], 1, v[4:5]
	v_lshl_add_u64 v[6:7], s[2:3], 0, v[4:5]
	s_mov_b64 s[2:3], 0x4000000
	v_lshl_add_u64 v[36:37], v[6:7], 0, s[2:3]
	v_ashrrev_i32_e32 v6, 2, v2
	s_movk_i32 s2, 0xffe0
	v_bfe_u32 v9, v2, 5, 1
	v_bfi_b32 v6, s2, v6, v2
	s_movk_i32 s2, 0x90
	v_lshl_add_u64 v[38:39], s[4:5], 0, v[4:5]
	v_and_b32_e32 v4, 0x5f, v2
	v_lshlrev_b32_e32 v5, 4, v9
	v_mul_lo_u32 v7, v6, s2
	v_add_u32_e32 v53, 0x8000, v6
	v_lshlrev_b32_e32 v6, 3, v9
	v_mul_lo_u32 v9, v52, s2
	v_lshl_add_u32 v54, v8, 4, v9
	v_mad_u32_u24 v55, v4, s2, v5
	v_and_or_b32 v56, v2, 64, v6
	s_lshl_b32 s2, s6, 7
	s_lshl_b32 s3, s8, 7
	v_add_u32_e32 v57, v7, v5

; __global__ void __launch_bounds__(256, 2) mega(Params p) {
;   __shared__ __attribute__((aligned(16))) char lds[LDS_BYTES];
	.amdhsa_kernel _Z4mega6Params
		.amdhsa_group_segment_fixed_size 77840
		.amdhsa_private_segment_fixed_size 0
		.amdhsa_kernarg_size 544
		.amdhsa_user_sgpr_count 2
		.amdhsa_user_sgpr_dispatch_ptr 0
		.amdhsa_user_sgpr_queue_ptr 0
		.amdhsa_user_sgpr_kernarg_segment_ptr 1
		.amdhsa_user_sgpr_dispatch_id 0
		.amdhsa_user_sgpr_kernarg_preload_length 0
		.amdhsa_user_sgpr_kernarg_preload_offset 0
		.amdhsa_user_sgpr_private_segment_size 0
		.amdhsa_uses_dynamic_stack 0
		.amdhsa_enable_private_segment 0
		.amdhsa_system_sgpr_workgroup_id_x 1
		.amdhsa_system_sgpr_workgroup_id_y 0
		.amdhsa_system_sgpr_workgroup_id_z 0
		.amdhsa_system_sgpr_workgroup_info 0
		.amdhsa_system_vgpr_workitem_id 0
		.amdhsa_next_free_vgpr 256
		.amdhsa_next_free_sgpr 100
		.amdhsa_accum_offset 256
		.amdhsa_reserve_vcc 1
		.amdhsa_float_round_mode_32 0
		.amdhsa_float_round_mode_16_64 0
		.amdhsa_float_denorm_mode_32 3
		.amdhsa_float_denorm_mode_16_64 3
		.amdhsa_dx10_clamp 1
		.amdhsa_ieee_mode 1
		.amdhsa_fp16_overflow 0
		.amdhsa_tg_split 0
		.amdhsa_exception_fp_ieee_invalid_op 0
		.amdhsa_exception_fp_denorm_src 0
		.amdhsa_exception_fp_ieee_div_zero 0
		.amdhsa_exception_fp_ieee_overflow 0
		.amdhsa_exception_fp_ieee_underflow 0
		.amdhsa_exception_fp_ieee_inexact 0
		.amdhsa_exception_int_div_zero 0
	.end_amdhsa_kernel

; __global__ void __launch_bounds__(256, 2) mega(Params p) {
;   __shared__ __attribute__((aligned(16))) char lds[LDS_BYTES];
amdhsa.kernels:
  - .agpr_count:     0
    .args:
      - .offset:         0
        .size:           288
        .value_kind:     by_value
      - .offset:         288
        .size:           4
        .value_kind:     hidden_block_count_x
      - .offset:         292
        .size:           4
        .value_kind:     hidden_block_count_y
      - .offset:         296
        .size:           4
        .value_kind:     hidden_block_count_z
      - .offset:         300
        .size:           2
        .value_kind:     hidden_group_size_x
      - .offset:         302
        .size:           2
        .value_kind:     hidden_group_size_y
      - .offset:         304
        .size:           2
        .value_kind:     hidden_group_size_z
      - .offset:         306
        .size:           2
        .value_kind:     hidden_remainder_x
      - .offset:         308
        .size:           2
        .value_kind:     hidden_remainder_y
      - .offset:         310
        .size:           2
        .value_kind:     hidden_remainder_z
      - .offset:         328
        .size:           8
        .value_kind:     hidden_global_offset_x
      - .offset:         336
        .size:           8
        .value_kind:     hidden_global_offset_y
      - .offset:         344
        .size:           8
        .value_kind:     hidden_global_offset_z
      - .offset:         352
        .size:           2
        .value_kind:     hidden_grid_dims
    .group_segment_fixed_size: 77840
    .kernarg_segment_align: 8
    .kernarg_segment_size: 544
    .language:       OpenCL C
    .language_version:
      - 2
      - 0
    .max_flat_workgroup_size: 256
    .name:           _Z4mega6Params
    .private_segment_fixed_size: 0
    .sgpr_count:     106
    .sgpr_spill_count: 366
    .symbol:         _Z4mega6Params.kd
    .uniform_work_group_size: 1
    .uses_dynamic_stack: false
    .vgpr_count:     256
    .vgpr_spill_count: 0
    .wavefront_size: 64
